# x loads with sc0 sc1 nt policy (system-scope streaming) in P0/P3
# speedup vs baseline: 1.0105x; 1.0020x over previous
.LBB0_38:
	s_add_i32 s28, s56, s58
	s_cmpk_lt_i32 s28, 0x4000
	s_cselect_b32 s16, s28, s56
	s_ashr_i32 s57, s56, 31
	s_lshl_b64 s[46:47], s[56:57], 12
	v_lshl_add_u64 v[34:35], v[2:3], 0, s[46:47]
	global_load_dwordx4 v[18:21], v[4:5], off
	s_ashr_i32 s17, s16, 31
	global_load_dwordx4 v[22:25], v[34:35], off sc0 sc1 nt
	global_load_dwordx4 v[26:29], v[34:35], off offset:1024 sc0 sc1 nt
	global_load_dwordx4 v[30:33], v[34:35], off offset:3072 sc0 sc1 nt
	s_nop 0
	global_load_dwordx4 v[34:37], v[34:35], off offset:2048 sc0 sc1 nt
	s_lshl_b64 s[0:1], s[56:57], 10
	s_lshl_b64 s[50:51], s[16:17], 12
	s_lshl_b64 s[46:47], s[16:17], 10
	v_lshl_add_u64 v[38:39], v[6:7], 0, s[0:1]
	v_lshl_add_u64 v[64:65], v[2:3], 0, s[50:51]
	global_load_dwordx4 v[38:41], v[38:39], off nt
	v_lshl_add_u64 v[66:67], v[6:7], 0, s[46:47]
	global_load_dwordx4 v[42:45], v[64:65], off sc0 sc1 nt
	global_load_dwordx4 v[46:49], v[64:65], off offset:1024 sc0 sc1 nt
	global_load_dwordx4 v[50:53], v[64:65], off offset:3072 sc0 sc1 nt
	global_load_dwordx4 v[54:57], v[64:65], off offset:2048 sc0 sc1 nt
	global_load_dwordx4 v[58:61], v[66:67], off nt
	s_lshl_b64 s[0:1], s[16:17], 11
	v_lshl_add_u64 v[68:69], v[8:9], 0, s[0:1]
	s_lshl_b64 s[48:49], s[56:57], 11
	v_lshl_add_u64 v[62:63], v[8:9], 0, s[48:49]
	s_waitcnt vmcnt(9)
	v_pk_mul_f32 v[64:65], v[24:25], v[24:25]
	v_pk_mul_f32 v[66:67], v[22:23], v[22:23]
	s_waitcnt vmcnt(8)
	v_pk_mul_f32 v[70:71], v[28:29], v[28:29]
	v_pk_mul_f32 v[72:73], v[26:27], v[26:27]
	s_waitcnt vmcnt(6)
	v_mul_f32_e32 v74, v35, v35
	v_mul_f32_e32 v76, v37, v37
	v_pk_mov_b32 v[78:79], v[66:67], v[64:65] op_sel:[1,0]
	v_mov_b32_e32 v67, v65
	s_waitcnt vmcnt(4)
	v_pk_mul_f32 v[64:65], v[44:45], v[44:45]
	v_pk_mul_f32 v[80:81], v[42:43], v[42:43]
	v_pk_mov_b32 v[82:83], v[72:73], v[70:71] op_sel:[1,0]
	v_mov_b32_e32 v73, v71
	s_waitcnt vmcnt(3)
	v_pk_mul_f32 v[70:71], v[48:49], v[48:49]
	v_pk_mul_f32 v[84:85], v[46:47], v[46:47]
	v_mul_f32_e32 v89, v32, v32
	v_mul_f32_e32 v90, v33, v33
	v_pk_fma_f32 v[74:75], v[34:35], v[34:35], v[74:75] op_sel_hi:[1,1,0]
	v_pk_fma_f32 v[76:77], v[36:37], v[36:37], v[76:77] op_sel_hi:[1,1,0]
	v_pk_add_f32 v[66:67], v[78:79], v[66:67]
	v_pk_mov_b32 v[78:79], v[80:81], v[64:65] op_sel:[1,0]
	v_mov_b32_e32 v81, v65
	v_pk_add_f32 v[64:65], v[82:83], v[72:73]
	v_pk_mov_b32 v[72:73], v[84:85], v[70:71] op_sel:[1,0]
	v_mov_b32_e32 v85, v71
	v_mul_f32_e32 v87, v31, v31
	s_waitcnt vmcnt(1)
	v_mul_f32_e32 v86, v55, v55
	v_mul_f32_e32 v88, v57, v57
	v_mov_b32_e32 v75, v89
	v_mov_b32_e32 v77, v90
	v_pk_add_f32 v[78:79], v[78:79], v[80:81]
	v_pk_add_f32 v[72:73], v[72:73], v[84:85]
	v_mul_f32_e32 v17, v30, v30
	v_mul_f32_e32 v91, v50, v50
	v_mul_f32_e32 v92, v51, v51
	v_mul_f32_e32 v93, v52, v52
	v_mul_f32_e32 v94, v53, v53
	v_pk_fma_f32 v[70:71], v[54:55], v[54:55], v[86:87] op_sel_hi:[1,1,0]
	v_pk_fma_f32 v[82:83], v[56:57], v[56:57], v[88:89] op_sel_hi:[1,1,0]
	v_pk_add_f32 v[66:67], v[66:67], v[66:67] op_sel:[0,1] op_sel_hi:[1,0]
	v_pk_add_f32 v[64:65], v[64:65], v[64:65] op_sel:[0,1] op_sel_hi:[1,0]
	v_pk_add_f32 v[74:75], v[74:75], v[76:77]
	v_pk_add_f32 v[76:77], v[78:79], v[78:79] op_sel:[0,1] op_sel_hi:[1,0]
	v_pk_add_f32 v[72:73], v[72:73], v[72:73] op_sel:[0,1] op_sel_hi:[1,0]
	v_mov_b32_e32 v71, v93
	v_mov_b32_e32 v83, v94
	v_mov_b32_e32 v67, v17
	v_mov_b32_e32 v65, v87
	v_mov_b32_e32 v77, v91
	v_mov_b32_e32 v73, v92
	v_pk_add_f32 v[70:71], v[70:71], v[82:83]
	v_pk_add_f32 v[64:65], v[66:67], v[64:65]
	v_pk_add_f32 v[66:67], v[76:77], v[72:73]
	v_pk_add_f32 v[64:65], v[64:65], v[74:75]
	v_pk_add_f32 v[66:67], v[66:67], v[70:71]
	v_mov_b32_e32 v71, v64
	v_mov_b32_e32 v70, v66
	v_mov_b32_e32 v64, v67
	v_pk_add_f32 v[64:65], v[70:71], v[64:65]
	ds_bpermute_b32 v67, v11, v65
	ds_bpermute_b32 v66, v11, v64
	s_waitcnt lgkmcnt(0)
	v_pk_add_f32 v[64:65], v[64:65], v[66:67]
	ds_bpermute_b32 v67, v12, v65
	ds_bpermute_b32 v66, v12, v64
	s_waitcnt lgkmcnt(0)
	v_pk_add_f32 v[64:65], v[64:65], v[66:67]
	ds_bpermute_b32 v67, v13, v65
	ds_bpermute_b32 v66, v13, v64
	s_waitcnt lgkmcnt(0)
	v_pk_add_f32 v[64:65], v[64:65], v[66:67]
	ds_bpermute_b32 v67, v14, v65
	ds_bpermute_b32 v66, v14, v64
	s_waitcnt lgkmcnt(0)
	v_pk_add_f32 v[64:65], v[64:65], v[66:67]
	ds_bpermute_b32 v67, v15, v65
	ds_bpermute_b32 v66, v15, v64
	s_waitcnt lgkmcnt(0)
	v_pk_add_f32 v[64:65], v[64:65], v[66:67]
	ds_bpermute_b32 v67, v16, v65
	ds_bpermute_b32 v66, v16, v64
	s_waitcnt lgkmcnt(0)
	v_pk_add_f32 v[64:65], v[64:65], v[66:67]
	s_nop 0
	v_pk_fma_f32 v[64:65], v[64:65], s[14:15], v[10:11] op_sel_hi:[1,0,0]
	s_nop 0
	v_mul_f32_e32 v17, 0x4b800000, v65
	v_cmp_gt_f32_e64 s[0:1], s15, v65
	v_mul_f32_e32 v66, 0x4b800000, v64
	v_cmp_gt_f32_e32 vcc, s15, v64
	v_cndmask_b32_e64 v17, v65, v17, s[0:1]
	v_rsq_f32_e32 v17, v17
	v_cndmask_b32_e32 v64, v64, v66, vcc
	v_rsq_f32_e32 v65, v64
	v_mul_f32_e32 v64, 0x45800000, v17
	v_cndmask_b32_e64 v64, v17, v64, s[0:1]
	v_mul_f32_e32 v66, 0x45800000, v65
	v_cndmask_b32_e32 v66, v65, v66, vcc
	v_pk_mul_f32 v[22:23], v[64:65], v[22:23] op_sel_hi:[0,1]
	v_pk_mul_f32 v[24:25], v[64:65], v[24:25] op_sel_hi:[0,1]
	v_pk_mul_f32 v[42:43], v[66:67], v[42:43] op_sel_hi:[0,1]
	v_pk_mul_f32 v[44:45], v[66:67], v[44:45] op_sel_hi:[0,1]
	v_pk_mul_f32 v[24:25], v[24:25], v[20:21]
	v_pk_mul_f32 v[22:23], v[22:23], v[18:19]
	v_pk_mul_f32 v[20:21], v[44:45], v[20:21]
	v_pk_mul_f32 v[18:19], v[42:43], v[18:19]
	v_cvt_pk_bf16_f32 v22, v22, v23
	v_cvt_pk_bf16_f32 v23, v24, v25
	v_cvt_pk_bf16_f32 v18, v18, v19
	v_cvt_pk_bf16_f32 v19, v20, v21
	global_store_dwordx2 v[62:63], v[22:23], off
	global_store_dwordx2 v[68:69], v[18:19], off
	global_load_dwordx4 v[18:21], v[4:5], off offset:1024
	v_pk_mul_f32 v[22:23], v[64:65], v[26:27] op_sel_hi:[0,1]
	v_pk_mul_f32 v[24:25], v[64:65], v[28:29] op_sel_hi:[0,1]
	v_pk_mul_f32 v[26:27], v[66:67], v[46:47] op_sel_hi:[0,1]
	v_pk_mul_f32 v[28:29], v[66:67], v[48:49] op_sel_hi:[0,1]
	s_lshl_b64 s[0:1], s[56:57], 9
	v_pk_mul_f32 v[30:31], v[64:65], v[30:31] op_sel_hi:[0,1]
	v_pk_mul_f32 v[32:33], v[64:65], v[32:33] op_sel_hi:[0,1]
	s_add_i32 s56, s28, s58
	s_waitcnt vmcnt(0)
	v_pk_mul_f32 v[24:25], v[24:25], v[20:21]
	v_pk_mul_f32 v[22:23], v[22:23], v[18:19]
	v_pk_mul_f32 v[20:21], v[28:29], v[20:21]
	v_pk_mul_f32 v[18:19], v[26:27], v[18:19]
	v_cvt_pk_bf16_f32 v22, v22, v23
	v_cvt_pk_bf16_f32 v23, v24, v25
	v_cvt_pk_bf16_f32 v18, v18, v19
	v_cvt_pk_bf16_f32 v19, v20, v21
	global_store_dwordx2 v[62:63], v[22:23], off offset:512
	global_store_dwordx2 v[68:69], v[18:19], off offset:512
	global_load_dwordx4 v[18:21], v[4:5], off offset:2048
	v_pk_mul_f32 v[22:23], v[64:65], v[34:35] op_sel_hi:[0,1]
	v_pk_mul_f32 v[24:25], v[64:65], v[36:37] op_sel_hi:[0,1]
	v_pk_mul_f32 v[26:27], v[66:67], v[54:55] op_sel_hi:[0,1]
	v_pk_mul_f32 v[28:29], v[66:67], v[56:57] op_sel_hi:[0,1]
	v_pk_mul_f32 v[34:35], v[66:67], v[50:51] op_sel_hi:[0,1]
	v_pk_mul_f32 v[36:37], v[66:67], v[52:53] op_sel_hi:[0,1]
	s_waitcnt vmcnt(0)
	v_pk_mul_f32 v[24:25], v[24:25], v[20:21]
	v_pk_mul_f32 v[22:23], v[22:23], v[18:19]
	v_pk_mul_f32 v[20:21], v[28:29], v[20:21]
	v_pk_mul_f32 v[18:19], v[26:27], v[18:19]
	v_cvt_pk_bf16_f32 v22, v22, v23
	v_cvt_pk_bf16_f32 v23, v24, v25
	v_cvt_pk_bf16_f32 v18, v18, v19
	v_cvt_pk_bf16_f32 v19, v20, v21
	global_store_dwordx2 v[62:63], v[22:23], off offset:1024
	global_store_dwordx2 v[68:69], v[18:19], off offset:1024
	global_load_dwordx4 v[18:21], v[4:5], off offset:3072
	v_lshl_add_u64 v[22:23], v[0:1], 0, s[0:1]
	s_lshl_b64 s[0:1], s[16:17], 9
	s_cmpk_gt_i32 s56, 0x3fff
	v_lshl_add_u64 v[24:25], v[0:1], 0, s[0:1]
	v_cvt_pk_bf16_f32 v26, v38, v39
	v_cvt_pk_bf16_f32 v27, v40, v41
	v_cvt_pk_bf16_f32 v28, v58, v59
	v_cvt_pk_bf16_f32 v29, v60, v61
	s_waitcnt vmcnt(0)
	v_pk_mul_f32 v[32:33], v[32:33], v[20:21]
	v_pk_mul_f32 v[30:31], v[30:31], v[18:19]
	v_pk_mul_f32 v[20:21], v[36:37], v[20:21]
	v_pk_mul_f32 v[18:19], v[34:35], v[18:19]
	v_cvt_pk_bf16_f32 v30, v30, v31
	v_cvt_pk_bf16_f32 v31, v32, v33
	v_cvt_pk_bf16_f32 v18, v18, v19
	v_cvt_pk_bf16_f32 v19, v20, v21
	global_store_dwordx2 v[62:63], v[30:31], off offset:1536
	global_store_dwordx2 v[68:69], v[18:19], off offset:1536
	global_store_dwordx2 v[22:23], v[26:27], off
	global_store_dwordx2 v[24:25], v[28:29], off
	s_cbranch_scc0 .LBB0_38

.LBB0_385:
	v_mov_b32_e32 v140, v144
	s_lshl_b32 s9, s44, 8
	v_readfirstlane_b32 s8, v140
	s_bfe_u32 s29, s8, 0x20006
	s_ashr_i32 s8, s8, 2
	s_andn2_b32 s8, s8, 63
	s_add_i32 s8, s8, s9
	v_and_or_b32 v142, v140, 15, s8
	s_lshl_b32 s8, s20, 8
	s_lshl_b32 s9, s29, 6
	v_bfe_u32 v149, v140, 4, 2
	s_or_b32 s8, s9, s8
	v_lshl_or_b32 v140, v149, 3, s8
	v_ashrrev_i32_e32 v143, 31, v142
	v_ashrrev_i32_e32 v141, 31, v140
	v_lshlrev_b64 v[150:151], 10, v[142:143]
	v_lshl_add_u64 v[158:159], v[150:151], 0, v[140:141]
	v_lshl_add_u64 v[160:161], v[158:159], 2, s[12:13]
	global_load_dwordx4 v[150:153], v[160:161], off sc0 sc1 nt
	global_load_dwordx4 v[154:157], v[160:161], off offset:16 sc0 sc1 nt
	v_lshl_add_u64 v[158:159], v[158:159], 1, s[16:17]
	s_lshl_b32 s44, s20, 2
	v_cmp_eq_u32_e32 vcc, 0, v149
	s_ashr_i32 s45, s44, 31
	s_waitcnt vmcnt(0)
	v_pk_add_f32 v[152:153], v[126:127], v[152:153]
	v_pk_add_f32 v[150:151], v[124:125], v[150:151]
	v_pk_add_f32 v[156:157], v[122:123], v[156:157]
	v_pk_add_f32 v[154:155], v[120:121], v[154:155]
	v_cvt_pk_bf16_f32 v120, v150, v151
	v_cvt_pk_bf16_f32 v121, v152, v153
	v_cvt_pk_bf16_f32 v122, v154, v155
	v_cvt_pk_bf16_f32 v123, v156, v157
	global_store_dwordx4 v[158:159], v[120:123], off
	global_load_dwordx4 v[120:123], v[160:161], off offset:128 sc0 sc1 nt
	s_nop 0
	global_load_dwordx4 v[124:127], v[160:161], off offset:144 sc0 sc1 nt
	v_mul_f32_e32 v151, v151, v151
	v_mul_f32_e32 v153, v153, v153
	v_mul_f32_e32 v155, v155, v155
	v_mul_f32_e32 v157, v157, v157
	v_fmac_f32_e32 v151, v150, v150
	v_fmac_f32_e32 v153, v152, v152
	v_fmac_f32_e32 v155, v154, v154
	v_fmac_f32_e32 v157, v156, v156
	v_add_f32_e32 v150, v151, v153
	v_add_f32_e32 v151, v155, v157
	v_add_f32_e32 v150, v150, v151
	s_waitcnt vmcnt(1)
	v_pk_add_f32 v[118:119], v[118:119], v[122:123]
	v_pk_add_f32 v[116:117], v[116:117], v[120:121]
	s_waitcnt vmcnt(0)
	v_pk_add_f32 v[120:121], v[114:115], v[126:127]
	v_pk_add_f32 v[122:123], v[112:113], v[124:125]
	v_mul_f32_e32 v112, v117, v117
	v_mul_f32_e32 v113, v119, v119
	v_mul_f32_e32 v114, v123, v123
	v_mul_f32_e32 v115, v121, v121
	v_fmac_f32_e32 v112, v116, v116
	v_fmac_f32_e32 v113, v118, v118
	v_fmac_f32_e32 v114, v122, v122
	v_fmac_f32_e32 v115, v120, v120
	v_add_f32_e32 v112, v112, v113
	v_add_f32_e32 v113, v114, v115
	v_add_f32_e32 v112, v112, v113
	v_add_f32_e32 v112, v150, v112
	ds_bpermute_b32 v113, v193, v112
	v_cvt_pk_bf16_f32 v114, v116, v117
	v_cvt_pk_bf16_f32 v115, v118, v119
	v_cvt_pk_bf16_f32 v116, v122, v123
	v_cvt_pk_bf16_f32 v117, v120, v121
	s_waitcnt lgkmcnt(0)
	v_add_f32_e32 v112, v112, v113
	ds_bpermute_b32 v113, v194, v112
	global_store_dwordx4 v[158:159], v[114:117], off offset:64
	s_and_saveexec_b64 s[46:47], vcc
	s_cbranch_execz .LBB0_387
	v_lshlrev_b64 v[114:115], 6, v[142:143]
	v_lshl_add_u64 v[114:115], s[6:7], 0, v[114:115]
	v_lshl_add_u64 v[114:115], s[44:45], 2, v[114:115]
	s_lshl_b32 s20, s29, 2
	v_lshl_add_u64 v[114:115], v[114:115], 0, s[20:21]
	s_waitcnt lgkmcnt(0)
	v_add_f32_e32 v112, v112, v113
	global_store_dword v[114:115], v112, off
.LBB0_387:
	s_or_b64 exec, exec, s[46:47]
	v_or_b32_e32 v112, 16, v142
	s_waitcnt lgkmcnt(0)
	v_ashrrev_i32_e32 v113, 31, v112
	v_lshlrev_b64 v[114:115], 10, v[112:113]
	v_lshl_add_u64 v[122:123], v[114:115], 0, v[140:141]
	v_lshl_add_u64 v[124:125], v[122:123], 2, s[12:13]
	global_load_dwordx4 v[114:117], v[124:125], off sc0 sc1 nt
	global_load_dwordx4 v[118:121], v[124:125], off offset:16 sc0 sc1 nt
	v_lshl_add_u64 v[122:123], v[122:123], 1, s[16:17]
	s_waitcnt vmcnt(1)
	v_pk_add_f32 v[116:117], v[110:111], v[116:117]
	v_pk_add_f32 v[114:115], v[108:109], v[114:115]
	s_waitcnt vmcnt(0)
	v_pk_add_f32 v[120:121], v[106:107], v[120:121]
	v_pk_add_f32 v[118:119], v[104:105], v[118:119]
	v_cvt_pk_bf16_f32 v104, v114, v115
	v_cvt_pk_bf16_f32 v105, v116, v117
	v_cvt_pk_bf16_f32 v106, v118, v119
	v_cvt_pk_bf16_f32 v107, v120, v121
	global_store_dwordx4 v[122:123], v[104:107], off
	global_load_dwordx4 v[104:107], v[124:125], off offset:128 sc0 sc1 nt
	s_nop 0
	global_load_dwordx4 v[108:111], v[124:125], off offset:144 sc0 sc1 nt
	v_mul_f32_e32 v115, v115, v115
	v_mul_f32_e32 v117, v117, v117
	v_mul_f32_e32 v119, v119, v119
	v_mul_f32_e32 v121, v121, v121
	v_fmac_f32_e32 v115, v114, v114
	v_fmac_f32_e32 v117, v116, v116
	v_fmac_f32_e32 v119, v118, v118
	v_fmac_f32_e32 v121, v120, v120
	v_add_f32_e32 v114, v115, v117
	v_add_f32_e32 v115, v119, v121
	v_add_f32_e32 v114, v114, v115
	s_waitcnt vmcnt(1)
	v_pk_add_f32 v[102:103], v[102:103], v[106:107]
	v_pk_add_f32 v[100:101], v[100:101], v[104:105]
	s_waitcnt vmcnt(0)
	v_pk_add_f32 v[104:105], v[98:99], v[110:111]
	v_pk_add_f32 v[106:107], v[96:97], v[108:109]
	v_mul_f32_e32 v96, v101, v101
	v_mul_f32_e32 v97, v103, v103
	v_mul_f32_e32 v98, v107, v107
	v_mul_f32_e32 v99, v105, v105
	v_fmac_f32_e32 v96, v100, v100
	v_fmac_f32_e32 v97, v102, v102
	v_fmac_f32_e32 v98, v106, v106
	v_fmac_f32_e32 v99, v104, v104
	v_add_f32_e32 v96, v96, v97
	v_add_f32_e32 v97, v98, v99
	v_add_f32_e32 v96, v96, v97
	v_add_f32_e32 v96, v114, v96
	ds_bpermute_b32 v97, v193, v96
	v_cvt_pk_bf16_f32 v98, v100, v101
	v_cvt_pk_bf16_f32 v99, v102, v103
	v_cvt_pk_bf16_f32 v100, v106, v107
	v_cvt_pk_bf16_f32 v101, v104, v105
	s_waitcnt lgkmcnt(0)
	v_add_f32_e32 v96, v96, v97
	ds_bpermute_b32 v97, v194, v96
	global_store_dwordx4 v[122:123], v[98:101], off offset:64
	s_and_saveexec_b64 s[46:47], vcc
	s_cbranch_execz .LBB0_389
	v_lshlrev_b64 v[98:99], 6, v[112:113]
	v_lshl_add_u64 v[98:99], s[6:7], 0, v[98:99]
	v_lshl_add_u64 v[98:99], s[44:45], 2, v[98:99]
	s_lshl_b32 s20, s29, 2
	v_lshl_add_u64 v[98:99], v[98:99], 0, s[20:21]
	s_waitcnt lgkmcnt(0)
	v_add_f32_e32 v96, v96, v97
	global_store_dword v[98:99], v96, off
.LBB0_389:
	s_or_b64 exec, exec, s[46:47]
	v_or_b32_e32 v96, 32, v142
	s_waitcnt lgkmcnt(0)
	v_ashrrev_i32_e32 v97, 31, v96
	v_lshlrev_b64 v[98:99], 10, v[96:97]
	v_lshl_add_u64 v[106:107], v[98:99], 0, v[140:141]
	v_lshl_add_u64 v[108:109], v[106:107], 2, s[12:13]
	global_load_dwordx4 v[98:101], v[108:109], off sc0 sc1 nt
	global_load_dwordx4 v[102:105], v[108:109], off offset:16 sc0 sc1 nt
	v_lshl_add_u64 v[106:107], v[106:107], 1, s[16:17]
	s_waitcnt vmcnt(1)
	v_pk_add_f32 v[100:101], v[94:95], v[100:101]
	v_pk_add_f32 v[98:99], v[92:93], v[98:99]
	s_waitcnt vmcnt(0)
	v_pk_add_f32 v[104:105], v[90:91], v[104:105]
	v_pk_add_f32 v[102:103], v[88:89], v[102:103]
	v_cvt_pk_bf16_f32 v88, v98, v99
	v_cvt_pk_bf16_f32 v89, v100, v101
	v_cvt_pk_bf16_f32 v90, v102, v103
	v_cvt_pk_bf16_f32 v91, v104, v105
	global_store_dwordx4 v[106:107], v[88:91], off
	global_load_dwordx4 v[88:91], v[108:109], off offset:128 sc0 sc1 nt
	s_nop 0
	global_load_dwordx4 v[92:95], v[108:109], off offset:144 sc0 sc1 nt
	v_mul_f32_e32 v99, v99, v99
	v_mul_f32_e32 v101, v101, v101
	v_mul_f32_e32 v103, v103, v103
	v_mul_f32_e32 v105, v105, v105
	v_fmac_f32_e32 v99, v98, v98
	v_fmac_f32_e32 v101, v100, v100
	v_fmac_f32_e32 v103, v102, v102
	v_fmac_f32_e32 v105, v104, v104
	v_add_f32_e32 v98, v99, v101
	v_add_f32_e32 v99, v103, v105
	v_add_f32_e32 v98, v98, v99
	s_waitcnt vmcnt(1)
	v_pk_add_f32 v[86:87], v[86:87], v[90:91]
	v_pk_add_f32 v[84:85], v[84:85], v[88:89]
	s_waitcnt vmcnt(0)
	v_pk_add_f32 v[88:89], v[82:83], v[94:95]
	v_pk_add_f32 v[90:91], v[80:81], v[92:93]
	v_mul_f32_e32 v80, v85, v85
	v_mul_f32_e32 v81, v87, v87
	v_mul_f32_e32 v82, v91, v91
	v_mul_f32_e32 v83, v89, v89
	v_fmac_f32_e32 v80, v84, v84
	v_fmac_f32_e32 v81, v86, v86
	v_fmac_f32_e32 v82, v90, v90
	v_fmac_f32_e32 v83, v88, v88
	v_add_f32_e32 v80, v80, v81
	v_add_f32_e32 v81, v82, v83
	v_add_f32_e32 v80, v80, v81
	v_add_f32_e32 v80, v98, v80
	ds_bpermute_b32 v81, v193, v80
	v_cvt_pk_bf16_f32 v82, v84, v85
	v_cvt_pk_bf16_f32 v83, v86, v87
	v_cvt_pk_bf16_f32 v84, v90, v91
	v_cvt_pk_bf16_f32 v85, v88, v89
	s_waitcnt lgkmcnt(0)
	v_add_f32_e32 v80, v80, v81
	ds_bpermute_b32 v81, v194, v80
	global_store_dwordx4 v[106:107], v[82:85], off offset:64
	s_and_saveexec_b64 s[46:47], vcc
	s_cbranch_execz .LBB0_391
	v_lshlrev_b64 v[82:83], 6, v[96:97]
	v_lshl_add_u64 v[82:83], s[6:7], 0, v[82:83]
	v_lshl_add_u64 v[82:83], s[44:45], 2, v[82:83]
	s_lshl_b32 s20, s29, 2
	v_lshl_add_u64 v[82:83], v[82:83], 0, s[20:21]
	s_waitcnt lgkmcnt(0)
	v_add_f32_e32 v80, v80, v81
	global_store_dword v[82:83], v80, off
.LBB0_391:
	s_or_b64 exec, exec, s[46:47]
	v_or_b32_e32 v80, 48, v142
	s_waitcnt lgkmcnt(0)
	v_ashrrev_i32_e32 v81, 31, v80
	v_lshlrev_b64 v[82:83], 10, v[80:81]
	v_lshl_add_u64 v[90:91], v[82:83], 0, v[140:141]
	v_lshl_add_u64 v[92:93], v[90:91], 2, s[12:13]
	global_load_dwordx4 v[82:85], v[92:93], off sc0 sc1 nt
	global_load_dwordx4 v[86:89], v[92:93], off offset:16 sc0 sc1 nt
	v_lshl_add_u64 v[90:91], v[90:91], 1, s[16:17]
	s_waitcnt vmcnt(1)
	v_pk_add_f32 v[84:85], v[78:79], v[84:85]
	v_pk_add_f32 v[82:83], v[76:77], v[82:83]
	s_waitcnt vmcnt(0)
	v_pk_add_f32 v[88:89], v[74:75], v[88:89]
	v_pk_add_f32 v[86:87], v[72:73], v[86:87]
	v_cvt_pk_bf16_f32 v72, v82, v83
	v_cvt_pk_bf16_f32 v73, v84, v85
	v_cvt_pk_bf16_f32 v74, v86, v87
	v_cvt_pk_bf16_f32 v75, v88, v89
	global_store_dwordx4 v[90:91], v[72:75], off
	global_load_dwordx4 v[72:75], v[92:93], off offset:128 sc0 sc1 nt
	s_nop 0
	global_load_dwordx4 v[76:79], v[92:93], off offset:144 sc0 sc1 nt
	v_mul_f32_e32 v83, v83, v83
	v_mul_f32_e32 v85, v85, v85
	v_mul_f32_e32 v87, v87, v87
	v_mul_f32_e32 v89, v89, v89
	v_fmac_f32_e32 v83, v82, v82
	v_fmac_f32_e32 v85, v84, v84
	v_fmac_f32_e32 v87, v86, v86
	v_fmac_f32_e32 v89, v88, v88
	v_add_f32_e32 v82, v83, v85
	v_add_f32_e32 v83, v87, v89
	v_add_f32_e32 v82, v82, v83
	s_waitcnt vmcnt(1)
	v_pk_add_f32 v[70:71], v[70:71], v[74:75]
	v_pk_add_f32 v[68:69], v[68:69], v[72:73]
	s_waitcnt vmcnt(0)
	v_pk_add_f32 v[72:73], v[66:67], v[78:79]
	v_pk_add_f32 v[74:75], v[64:65], v[76:77]
	v_mul_f32_e32 v64, v69, v69
	v_mul_f32_e32 v65, v71, v71
	v_mul_f32_e32 v66, v75, v75
	v_mul_f32_e32 v67, v73, v73
	v_fmac_f32_e32 v64, v68, v68
	v_fmac_f32_e32 v65, v70, v70
	v_fmac_f32_e32 v66, v74, v74
	v_fmac_f32_e32 v67, v72, v72
	v_add_f32_e32 v64, v64, v65
	v_add_f32_e32 v65, v66, v67
	v_add_f32_e32 v64, v64, v65
	v_add_f32_e32 v64, v82, v64
	ds_bpermute_b32 v65, v193, v64
	v_cvt_pk_bf16_f32 v66, v68, v69
	v_cvt_pk_bf16_f32 v67, v70, v71
	v_cvt_pk_bf16_f32 v68, v74, v75
	v_cvt_pk_bf16_f32 v69, v72, v73
	s_waitcnt lgkmcnt(0)
	v_add_f32_e32 v64, v64, v65
	ds_bpermute_b32 v65, v194, v64
	global_store_dwordx4 v[90:91], v[66:69], off offset:64
	s_and_saveexec_b64 s[46:47], vcc
	s_cbranch_execz .LBB0_393
	v_lshlrev_b64 v[66:67], 6, v[80:81]
	v_lshl_add_u64 v[66:67], s[6:7], 0, v[66:67]
	v_lshl_add_u64 v[66:67], s[44:45], 2, v[66:67]
	s_lshl_b32 s20, s29, 2
	v_lshl_add_u64 v[66:67], v[66:67], 0, s[20:21]
	s_waitcnt lgkmcnt(0)
	v_add_f32_e32 v64, v64, v65
	global_store_dword v[66:67], v64, off
.LBB0_393:
	s_or_b64 exec, exec, s[46:47]
	v_add_u32_e32 v64, 0x80, v142
	s_waitcnt lgkmcnt(0)
	v_ashrrev_i32_e32 v65, 31, v64
	v_lshlrev_b64 v[66:67], 10, v[64:65]
	v_lshl_add_u64 v[74:75], v[66:67], 0, v[140:141]
	v_lshl_add_u64 v[76:77], v[74:75], 2, s[12:13]
	global_load_dwordx4 v[66:69], v[76:77], off sc0 sc1 nt
	global_load_dwordx4 v[70:73], v[76:77], off offset:16 sc0 sc1 nt
	v_lshl_add_u64 v[74:75], v[74:75], 1, s[16:17]
	s_waitcnt vmcnt(1)
	v_pk_add_f32 v[68:69], v[62:63], v[68:69]
	v_pk_add_f32 v[66:67], v[60:61], v[66:67]
	s_waitcnt vmcnt(0)
	v_pk_add_f32 v[72:73], v[58:59], v[72:73]
	v_pk_add_f32 v[70:71], v[56:57], v[70:71]
	v_cvt_pk_bf16_f32 v56, v66, v67
	v_cvt_pk_bf16_f32 v57, v68, v69
	v_cvt_pk_bf16_f32 v58, v70, v71
	v_cvt_pk_bf16_f32 v59, v72, v73
	global_store_dwordx4 v[74:75], v[56:59], off
	global_load_dwordx4 v[56:59], v[76:77], off offset:128 sc0 sc1 nt
	s_nop 0
	global_load_dwordx4 v[60:63], v[76:77], off offset:144 sc0 sc1 nt
	v_mul_f32_e32 v67, v67, v67
	v_mul_f32_e32 v69, v69, v69
	v_mul_f32_e32 v71, v71, v71
	v_mul_f32_e32 v73, v73, v73
	v_fmac_f32_e32 v67, v66, v66
	v_fmac_f32_e32 v69, v68, v68
	v_fmac_f32_e32 v71, v70, v70
	v_fmac_f32_e32 v73, v72, v72
	v_add_f32_e32 v66, v67, v69
	v_add_f32_e32 v67, v71, v73
	v_add_f32_e32 v66, v66, v67
	s_waitcnt vmcnt(1)
	v_pk_add_f32 v[54:55], v[54:55], v[58:59]
	v_pk_add_f32 v[52:53], v[52:53], v[56:57]
	s_waitcnt vmcnt(0)
	v_pk_add_f32 v[56:57], v[50:51], v[62:63]
	v_pk_add_f32 v[58:59], v[48:49], v[60:61]
	v_mul_f32_e32 v48, v53, v53
	v_mul_f32_e32 v49, v55, v55
	v_mul_f32_e32 v50, v59, v59
	v_mul_f32_e32 v51, v57, v57
	v_fmac_f32_e32 v48, v52, v52
	v_fmac_f32_e32 v49, v54, v54
	v_fmac_f32_e32 v50, v58, v58
	v_fmac_f32_e32 v51, v56, v56
	v_add_f32_e32 v48, v48, v49
	v_add_f32_e32 v49, v50, v51
	v_add_f32_e32 v48, v48, v49
	v_add_f32_e32 v48, v66, v48
	ds_bpermute_b32 v49, v193, v48
	v_cvt_pk_bf16_f32 v50, v52, v53
	v_cvt_pk_bf16_f32 v51, v54, v55
	v_cvt_pk_bf16_f32 v52, v58, v59
	v_cvt_pk_bf16_f32 v53, v56, v57
	s_waitcnt lgkmcnt(0)
	v_add_f32_e32 v48, v48, v49
	ds_bpermute_b32 v49, v194, v48
	global_store_dwordx4 v[74:75], v[50:53], off offset:64
	s_and_saveexec_b64 s[46:47], vcc
	s_cbranch_execz .LBB0_395
	v_lshlrev_b64 v[50:51], 6, v[64:65]
	v_lshl_add_u64 v[50:51], s[6:7], 0, v[50:51]
	v_lshl_add_u64 v[50:51], s[44:45], 2, v[50:51]
	s_lshl_b32 s20, s29, 2
	v_lshl_add_u64 v[50:51], v[50:51], 0, s[20:21]
	s_waitcnt lgkmcnt(0)
	v_add_f32_e32 v48, v48, v49
	global_store_dword v[50:51], v48, off
.LBB0_395:
	s_or_b64 exec, exec, s[46:47]
	v_add_u32_e32 v48, 0x90, v142
	s_waitcnt lgkmcnt(0)
	v_ashrrev_i32_e32 v49, 31, v48
	v_lshlrev_b64 v[50:51], 10, v[48:49]
	v_lshl_add_u64 v[58:59], v[50:51], 0, v[140:141]
	v_lshl_add_u64 v[60:61], v[58:59], 2, s[12:13]
	global_load_dwordx4 v[50:53], v[60:61], off sc0 sc1 nt
	global_load_dwordx4 v[54:57], v[60:61], off offset:16 sc0 sc1 nt
	v_lshl_add_u64 v[58:59], v[58:59], 1, s[16:17]
	s_waitcnt vmcnt(1)
	v_pk_add_f32 v[52:53], v[46:47], v[52:53]
	v_pk_add_f32 v[50:51], v[44:45], v[50:51]
	s_waitcnt vmcnt(0)
	v_pk_add_f32 v[56:57], v[42:43], v[56:57]
	v_pk_add_f32 v[54:55], v[40:41], v[54:55]
	v_cvt_pk_bf16_f32 v40, v50, v51
	v_cvt_pk_bf16_f32 v41, v52, v53
	v_cvt_pk_bf16_f32 v42, v54, v55
	v_cvt_pk_bf16_f32 v43, v56, v57
	global_store_dwordx4 v[58:59], v[40:43], off
	global_load_dwordx4 v[40:43], v[60:61], off offset:128 sc0 sc1 nt
	s_nop 0
	global_load_dwordx4 v[44:47], v[60:61], off offset:144 sc0 sc1 nt
	v_mul_f32_e32 v51, v51, v51
	v_mul_f32_e32 v53, v53, v53
	v_mul_f32_e32 v55, v55, v55
	v_mul_f32_e32 v57, v57, v57
	v_fmac_f32_e32 v51, v50, v50
	v_fmac_f32_e32 v53, v52, v52
	v_fmac_f32_e32 v55, v54, v54
	v_fmac_f32_e32 v57, v56, v56
	v_add_f32_e32 v50, v51, v53
	v_add_f32_e32 v51, v55, v57
	v_add_f32_e32 v50, v50, v51
	s_waitcnt vmcnt(1)
	v_pk_add_f32 v[38:39], v[38:39], v[42:43]
	v_pk_add_f32 v[36:37], v[36:37], v[40:41]
	s_waitcnt vmcnt(0)
	v_pk_add_f32 v[40:41], v[34:35], v[46:47]
	v_pk_add_f32 v[42:43], v[32:33], v[44:45]
	v_mul_f32_e32 v32, v37, v37
	v_mul_f32_e32 v33, v39, v39
	v_mul_f32_e32 v34, v43, v43
	v_mul_f32_e32 v35, v41, v41
	v_fmac_f32_e32 v32, v36, v36
	v_fmac_f32_e32 v33, v38, v38
	v_fmac_f32_e32 v34, v42, v42
	v_fmac_f32_e32 v35, v40, v40
	v_add_f32_e32 v32, v32, v33
	v_add_f32_e32 v33, v34, v35
	v_add_f32_e32 v32, v32, v33
	v_add_f32_e32 v32, v50, v32
	ds_bpermute_b32 v33, v193, v32
	v_cvt_pk_bf16_f32 v34, v36, v37
	v_cvt_pk_bf16_f32 v35, v38, v39
	v_cvt_pk_bf16_f32 v36, v42, v43
	v_cvt_pk_bf16_f32 v37, v40, v41
	s_waitcnt lgkmcnt(0)
	v_add_f32_e32 v32, v32, v33
	ds_bpermute_b32 v33, v194, v32
	global_store_dwordx4 v[58:59], v[34:37], off offset:64
	s_and_saveexec_b64 s[46:47], vcc
	s_cbranch_execz .LBB0_397
	v_lshlrev_b64 v[34:35], 6, v[48:49]
	v_lshl_add_u64 v[34:35], s[6:7], 0, v[34:35]
	v_lshl_add_u64 v[34:35], s[44:45], 2, v[34:35]
	s_lshl_b32 s20, s29, 2
	v_lshl_add_u64 v[34:35], v[34:35], 0, s[20:21]
	s_waitcnt lgkmcnt(0)
	v_add_f32_e32 v32, v32, v33
	global_store_dword v[34:35], v32, off
.LBB0_397:
	s_or_b64 exec, exec, s[46:47]
	v_add_u32_e32 v32, 0xa0, v142
	s_waitcnt lgkmcnt(0)
	v_ashrrev_i32_e32 v33, 31, v32
	v_lshlrev_b64 v[34:35], 10, v[32:33]
	v_lshl_add_u64 v[42:43], v[34:35], 0, v[140:141]
	v_lshl_add_u64 v[44:45], v[42:43], 2, s[12:13]
	global_load_dwordx4 v[34:37], v[44:45], off sc0 sc1 nt
	global_load_dwordx4 v[38:41], v[44:45], off offset:16 sc0 sc1 nt
	v_lshl_add_u64 v[42:43], v[42:43], 1, s[16:17]
	s_waitcnt vmcnt(1)
	v_pk_add_f32 v[36:37], v[30:31], v[36:37]
	v_pk_add_f32 v[34:35], v[28:29], v[34:35]
	s_waitcnt vmcnt(0)
	v_pk_add_f32 v[40:41], v[26:27], v[40:41]
	v_pk_add_f32 v[38:39], v[24:25], v[38:39]
	v_cvt_pk_bf16_f32 v24, v34, v35
	v_cvt_pk_bf16_f32 v25, v36, v37
	v_cvt_pk_bf16_f32 v26, v38, v39
	v_cvt_pk_bf16_f32 v27, v40, v41
	global_store_dwordx4 v[42:43], v[24:27], off
	global_load_dwordx4 v[24:27], v[44:45], off offset:128 sc0 sc1 nt
	s_nop 0
	global_load_dwordx4 v[28:31], v[44:45], off offset:144 sc0 sc1 nt
	v_mul_f32_e32 v35, v35, v35
	v_mul_f32_e32 v37, v37, v37
	v_mul_f32_e32 v39, v39, v39
	v_mul_f32_e32 v41, v41, v41
	v_fmac_f32_e32 v35, v34, v34
	v_fmac_f32_e32 v37, v36, v36
	v_fmac_f32_e32 v39, v38, v38
	v_fmac_f32_e32 v41, v40, v40
	v_add_f32_e32 v34, v35, v37
	v_add_f32_e32 v35, v39, v41
	v_add_f32_e32 v34, v34, v35
	s_waitcnt vmcnt(1)
	v_pk_add_f32 v[22:23], v[22:23], v[26:27]
	v_pk_add_f32 v[20:21], v[20:21], v[24:25]
	s_waitcnt vmcnt(0)
	v_pk_add_f32 v[24:25], v[18:19], v[30:31]
	v_pk_add_f32 v[26:27], v[16:17], v[28:29]
	v_mul_f32_e32 v16, v21, v21
	v_mul_f32_e32 v17, v23, v23
	v_mul_f32_e32 v18, v27, v27
	v_mul_f32_e32 v19, v25, v25
	v_fmac_f32_e32 v16, v20, v20
	v_fmac_f32_e32 v17, v22, v22
	v_fmac_f32_e32 v18, v26, v26
	v_fmac_f32_e32 v19, v24, v24
	v_add_f32_e32 v16, v16, v17
	v_add_f32_e32 v17, v18, v19
	v_add_f32_e32 v16, v16, v17
	v_add_f32_e32 v16, v34, v16
	ds_bpermute_b32 v17, v193, v16
	v_cvt_pk_bf16_f32 v18, v20, v21
	v_cvt_pk_bf16_f32 v19, v22, v23
	v_cvt_pk_bf16_f32 v20, v26, v27
	v_cvt_pk_bf16_f32 v21, v24, v25
	s_waitcnt lgkmcnt(0)
	v_add_f32_e32 v16, v16, v17
	ds_bpermute_b32 v17, v194, v16
	global_store_dwordx4 v[42:43], v[18:21], off offset:64
	s_and_saveexec_b64 s[46:47], vcc
	s_cbranch_execz .LBB0_399
	v_lshlrev_b64 v[18:19], 6, v[32:33]
	v_lshl_add_u64 v[18:19], s[6:7], 0, v[18:19]
	v_lshl_add_u64 v[18:19], s[44:45], 2, v[18:19]
	s_lshl_b32 s20, s29, 2
	v_lshl_add_u64 v[18:19], v[18:19], 0, s[20:21]
	s_waitcnt lgkmcnt(0)
	v_add_f32_e32 v16, v16, v17
	global_store_dword v[18:19], v16, off
.LBB0_399:
	s_or_b64 exec, exec, s[46:47]
	v_add_u32_e32 v16, 0xb0, v142
	s_waitcnt lgkmcnt(0)
	v_ashrrev_i32_e32 v17, 31, v16
	v_lshlrev_b64 v[18:19], 10, v[16:17]
	v_lshl_add_u64 v[26:27], v[18:19], 0, v[140:141]
	v_lshl_add_u64 v[28:29], v[26:27], 2, s[12:13]
	global_load_dwordx4 v[18:21], v[28:29], off sc0 sc1 nt
	global_load_dwordx4 v[22:25], v[28:29], off offset:16 sc0 sc1 nt
	v_lshl_add_u64 v[26:27], v[26:27], 1, s[16:17]
	s_waitcnt vmcnt(1)
	v_pk_add_f32 v[20:21], v[14:15], v[20:21]
	v_pk_add_f32 v[18:19], v[12:13], v[18:19]
	s_waitcnt vmcnt(0)
	v_pk_add_f32 v[24:25], v[10:11], v[24:25]
	v_pk_add_f32 v[22:23], v[8:9], v[22:23]
	v_cvt_pk_bf16_f32 v8, v18, v19
	v_cvt_pk_bf16_f32 v9, v20, v21
	v_cvt_pk_bf16_f32 v10, v22, v23
	v_cvt_pk_bf16_f32 v11, v24, v25
	global_store_dwordx4 v[26:27], v[8:11], off
	global_load_dwordx4 v[8:11], v[28:29], off offset:128 sc0 sc1 nt
	s_nop 0
	global_load_dwordx4 v[12:15], v[28:29], off offset:144 sc0 sc1 nt
	v_mul_f32_e32 v19, v19, v19
	v_mul_f32_e32 v21, v21, v21
	v_mul_f32_e32 v23, v23, v23
	v_mul_f32_e32 v25, v25, v25
	v_fmac_f32_e32 v19, v18, v18
	v_fmac_f32_e32 v21, v20, v20
	v_fmac_f32_e32 v23, v22, v22
	v_fmac_f32_e32 v25, v24, v24
	v_add_f32_e32 v18, v19, v21
	v_add_f32_e32 v19, v23, v25
	v_add_f32_e32 v18, v18, v19
	s_waitcnt vmcnt(1)
	v_pk_add_f32 v[6:7], v[6:7], v[10:11]
	v_pk_add_f32 v[4:5], v[4:5], v[8:9]
	s_waitcnt vmcnt(0)
	v_pk_add_f32 v[8:9], v[2:3], v[14:15]
	v_pk_add_f32 v[10:11], v[0:1], v[12:13]
	v_mul_f32_e32 v0, v5, v5
	v_mul_f32_e32 v1, v7, v7
	v_mul_f32_e32 v2, v11, v11
	v_mul_f32_e32 v3, v9, v9
	v_fmac_f32_e32 v0, v4, v4
	v_fmac_f32_e32 v1, v6, v6
	v_fmac_f32_e32 v2, v10, v10
	v_fmac_f32_e32 v3, v8, v8
	v_add_f32_e32 v0, v0, v1
	v_add_f32_e32 v1, v2, v3
	v_add_f32_e32 v0, v0, v1
	v_add_f32_e32 v0, v18, v0
	ds_bpermute_b32 v1, v193, v0
	v_cvt_pk_bf16_f32 v2, v4, v5
	v_cvt_pk_bf16_f32 v3, v6, v7
	v_cvt_pk_bf16_f32 v4, v10, v11
	v_cvt_pk_bf16_f32 v5, v8, v9
	s_waitcnt lgkmcnt(0)
	v_add_f32_e32 v0, v0, v1
	ds_bpermute_b32 v1, v194, v0
	global_store_dwordx4 v[26:27], v[2:5], off offset:64
	s_and_saveexec_b64 s[46:47], vcc
	s_cbranch_execz .LBB0_401
	v_lshlrev_b64 v[2:3], 6, v[16:17]
	v_lshl_add_u64 v[2:3], s[6:7], 0, v[2:3]
	v_lshl_add_u64 v[2:3], s[44:45], 2, v[2:3]
	s_lshl_b32 s20, s29, 2
	v_lshl_add_u64 v[2:3], v[2:3], 0, s[20:21]
	s_waitcnt lgkmcnt(0)
	v_add_f32_e32 v0, v0, v1
	global_store_dword v[2:3], v0, off
